# MLA steady loop, non-diagonal tiles: block 0 row-max partial and its 16 exp2 issued between block 1's S MFMAs; rescale path multiplies block 0 probabilities by alpha
# baseline (speedup 1.0000x reference)
; template <int DQK, int W1, int DV, int VW, int MODE> ...
;     ...
;       pv_block<0>(o[0], bufa + vlane, pb);
;       if constexpr (NCB > 1) pv_block<1>(o[1], bufa + vlane, pb);
;       if constexpr (NCB > 2) pv_block<2>(o[2], bufa + vlane, pb);
;       if constexpr (NCB > 3) pv_block<3>(o[3], bufa + vlane, pb);
;     }
;     asm volatile("s_waitcnt vmcnt(0)" ::: "memory");
;     __syncthreads();
.Lmla_join:
	s_cmp_lt_u32 s26, 0x1000
	s_cbranch_scc1 .Lmla_pv
	s_waitcnt vmcnt(0)
	s_barrier

; DI int crow(int reg, int hi) { return (reg & 3) + 8 * (reg >> 2) + 4 * hi; }
; template <int DQK, int W1, int DV, int VW, int MODE> ...
;     ...
;     if (!(MODE == 0 && kb > tq0 + 31)) {
;       f32x16 s[2];
;       s[0] = s_block<KSTR, ND, 0>(bufa + klane, qf, negm);
;       s[1] = s_block<KSTR, ND, 1>(bufa + klane, qf, negm);
;       if (MODE == 0) {
;         if (__builtin_amdgcn_readfirstlane((int)(kb + 63 > tq0))) {
; #pragma unroll
;           for (int n = 0; n < 2; ++n)
; #pragma unroll
;             for (int i = 0; i < 16; ++i) { const int key = kb + 32 * n + crow(i, hi); if (key > tq) s[n][i] = NEGV; }
;         }
.LBB0_1405:
	s_sub_i32 s30, s69, 63
	s_cmp_gt_i32 s30, s0
	s_cbranch_scc1 .Lmla_dobar
	s_mov_b32 s31, 0
	s_mov_b32 s70, s100
	v_add_u32_e32 v14, s70, v189
	s_cmp_le_i32 s69, s54
	s_cbranch_scc1 .Lmla_nd
	ds_read_b128 v[2:5], v14
	ds_read_b128 v[6:9], v14 offset:32
	ds_read_b128 v[10:13], v14 offset:64
	ds_read_b128 v[112:115], v14 offset:96
	s_waitcnt lgkmcnt(3)
	v_mfma_f32_32x32x16_bf16 v[96:111], v[2:5], v[128:131], v[80:95]
	ds_read_b128 v[2:5], v14 offset:128
	s_waitcnt lgkmcnt(3)
	v_mfma_f32_32x32x16_bf16 v[96:111], v[6:9], v[132:135], v[96:111]
	ds_read_b128 v[6:9], v14 offset:160
	s_waitcnt lgkmcnt(3)
	v_mfma_f32_32x32x16_bf16 v[96:111], v[10:13], v[136:139], v[96:111]
	ds_read_b128 v[10:13], v14 offset:192
	s_waitcnt lgkmcnt(3)
	v_mfma_f32_32x32x16_bf16 v[96:111], v[112:115], v[140:143], v[96:111]
	ds_read_b128 v[112:115], v14 offset:224
	s_waitcnt lgkmcnt(3)
	v_mfma_f32_32x32x16_bf16 v[96:111], v[2:5], v[144:147], v[96:111]
	ds_read_b128 v[2:5], v14 offset:256
	s_waitcnt lgkmcnt(3)
	v_mfma_f32_32x32x16_bf16 v[96:111], v[6:9], v[148:151], v[96:111]
	ds_read_b128 v[6:9], v14 offset:288
	s_waitcnt lgkmcnt(3)
	v_mfma_f32_32x32x16_bf16 v[96:111], v[10:13], v[152:155], v[96:111]
	ds_read_b128 v[10:13], v14 offset:320
	s_waitcnt lgkmcnt(3)
	v_mfma_f32_32x32x16_bf16 v[96:111], v[112:115], v[156:159], v[96:111]
	ds_read_b128 v[112:115], v14 offset:352
	s_waitcnt lgkmcnt(3)
	v_mfma_f32_32x32x16_bf16 v[96:111], v[2:5], v[160:163], v[96:111]
	ds_read_b128 v[2:5], v14 offset:12800
	s_waitcnt lgkmcnt(3)
	v_mfma_f32_32x32x16_bf16 v[96:111], v[6:9], v[164:167], v[96:111]
	ds_read_b128 v[6:9], v14 offset:12832
	s_waitcnt lgkmcnt(3)
	v_mfma_f32_32x32x16_bf16 v[96:111], v[10:13], v[168:171], v[96:111]
	ds_read_b128 v[10:13], v14 offset:12864
	s_waitcnt lgkmcnt(3)
	v_mfma_f32_32x32x16_bf16 v[96:111], v[112:115], v[172:175], v[96:111]
	ds_read_b128 v[208:211], v14 offset:12896
	s_waitcnt lgkmcnt(3)
	v_mfma_f32_32x32x16_bf16 v[112:127], v[2:5], v[128:131], v[80:95]
	ds_read_b128 v[2:5], v14 offset:12928
	s_waitcnt lgkmcnt(3)
	v_mfma_f32_32x32x16_bf16 v[112:127], v[6:9], v[132:135], v[112:127]
	ds_read_b128 v[6:9], v14 offset:12960
	s_waitcnt lgkmcnt(3)
	v_mfma_f32_32x32x16_bf16 v[112:127], v[10:13], v[136:139], v[112:127]
	ds_read_b128 v[10:13], v14 offset:12992
	s_waitcnt lgkmcnt(3)
	v_mfma_f32_32x32x16_bf16 v[112:127], v[208:211], v[140:143], v[112:127]
	ds_read_b128 v[208:211], v14 offset:13024
	s_waitcnt lgkmcnt(3)
	v_mfma_f32_32x32x16_bf16 v[112:127], v[2:5], v[144:147], v[112:127]
	ds_read_b128 v[2:5], v14 offset:13056
	s_waitcnt lgkmcnt(3)
	v_mfma_f32_32x32x16_bf16 v[112:127], v[6:9], v[148:151], v[112:127]
	ds_read_b128 v[6:9], v14 offset:13088
	s_waitcnt lgkmcnt(3)
	v_mfma_f32_32x32x16_bf16 v[112:127], v[10:13], v[152:155], v[112:127]
	ds_read_b128 v[10:13], v14 offset:13120
	s_waitcnt lgkmcnt(3)
	v_mfma_f32_32x32x16_bf16 v[112:127], v[208:211], v[156:159], v[112:127]
	ds_read_b128 v[208:211], v14 offset:13152
	s_waitcnt lgkmcnt(3)
	v_mfma_f32_32x32x16_bf16 v[112:127], v[2:5], v[160:163], v[112:127]
	s_waitcnt lgkmcnt(2)
	v_mfma_f32_32x32x16_bf16 v[112:127], v[6:9], v[164:167], v[112:127]
	s_waitcnt lgkmcnt(1)
	v_mfma_f32_32x32x16_bf16 v[112:127], v[10:13], v[168:171], v[112:127]
	s_waitcnt lgkmcnt(0)
	v_mfma_f32_32x32x16_bf16 v[112:127], v[208:211], v[172:175], v[112:127]
	s_cmp_le_i32 s69, s54
	s_cbranch_scc1 .LBB0_1408
	v_add_u32_e32 v2, s69, v188
	v_subrev_u32_e32 v3, 63, v2
	v_cmp_gt_i32_e32 vcc, v3, v186
	s_nop 1
	v_cndmask_b32_e32 v4, v96, v232, vcc
	v_cmp_lt_i32_e32 vcc, v3, v186
	v_subrev_u32_e32 v3, 61, v2
	s_nop 0
	v_cndmask_b32_e32 v96, v4, v96, vcc
	v_cndmask_b32_e32 v97, v232, v97, vcc
	v_cmp_le_i32_e32 vcc, v3, v186
	v_subrev_u32_e32 v3, 60, v2
	s_nop 0
	v_cndmask_b32_e32 v98, v232, v98, vcc
	v_cmp_le_i32_e32 vcc, v3, v186
	v_subrev_u32_e32 v3, 55, v2
	s_nop 0
	v_cndmask_b32_e32 v99, v232, v99, vcc
	v_cmp_le_i32_e32 vcc, v3, v186
	v_subrev_u32_e32 v3, 54, v2
	s_nop 0
	v_cndmask_b32_e32 v100, v232, v100, vcc
	v_cmp_le_i32_e32 vcc, v3, v186
	v_subrev_u32_e32 v3, 53, v2
	s_nop 0
	v_cndmask_b32_e32 v101, v232, v101, vcc
	v_cmp_le_i32_e32 vcc, v3, v186
	v_subrev_u32_e32 v3, 52, v2
	s_nop 0
	v_cndmask_b32_e32 v102, v232, v102, vcc
	v_cmp_le_i32_e32 vcc, v3, v186
	v_subrev_u32_e32 v3, 47, v2
	s_nop 0
	v_cndmask_b32_e32 v103, v232, v103, vcc
	v_cmp_le_i32_e32 vcc, v3, v186
	v_subrev_u32_e32 v3, 46, v2
	s_nop 0
	v_cndmask_b32_e32 v104, v232, v104, vcc
	v_cmp_le_i32_e32 vcc, v3, v186
	v_subrev_u32_e32 v3, 45, v2
	s_nop 0
	v_cndmask_b32_e32 v105, v232, v105, vcc
	v_cmp_le_i32_e32 vcc, v3, v186
	v_subrev_u32_e32 v3, 44, v2
	s_nop 0
	v_cndmask_b32_e32 v106, v232, v106, vcc
	v_cmp_le_i32_e32 vcc, v3, v186
	v_subrev_u32_e32 v3, 39, v2
	s_nop 0
	v_cndmask_b32_e32 v107, v232, v107, vcc
	v_cmp_le_i32_e32 vcc, v3, v186
	v_subrev_u32_e32 v3, 38, v2
	s_nop 0
	v_cndmask_b32_e32 v108, v232, v108, vcc
	v_cmp_le_i32_e32 vcc, v3, v186
	v_subrev_u32_e32 v3, 37, v2
	s_nop 0
	v_cndmask_b32_e32 v109, v232, v109, vcc
	v_cmp_le_i32_e32 vcc, v3, v186
	v_subrev_u32_e32 v3, 36, v2
	s_nop 0
	v_cndmask_b32_e32 v110, v232, v110, vcc
	v_cmp_le_i32_e32 vcc, v3, v186
	v_subrev_u32_e32 v3, 31, v2
	s_nop 0
	v_cndmask_b32_e32 v111, v232, v111, vcc
	v_cmp_le_i32_e32 vcc, v3, v186
	v_subrev_u32_e32 v3, 30, v2
	s_nop 0
	v_cndmask_b32_e32 v112, v232, v112, vcc
	v_cmp_le_i32_e32 vcc, v3, v186
	v_subrev_u32_e32 v3, 29, v2
	s_nop 0
	v_cndmask_b32_e32 v113, v232, v113, vcc
	v_cmp_le_i32_e32 vcc, v3, v186
	v_subrev_u32_e32 v3, 28, v2
	s_nop 0
	v_cndmask_b32_e32 v114, v232, v114, vcc
	v_cmp_le_i32_e32 vcc, v3, v186
	v_subrev_u32_e32 v3, 23, v2
	s_nop 0
	v_cndmask_b32_e32 v115, v232, v115, vcc
	v_cmp_le_i32_e32 vcc, v3, v186
	v_subrev_u32_e32 v3, 22, v2
	s_nop 0
	v_cndmask_b32_e32 v116, v232, v116, vcc
	v_cmp_le_i32_e32 vcc, v3, v186
	v_subrev_u32_e32 v3, 21, v2
	s_nop 0
	v_cndmask_b32_e32 v117, v232, v117, vcc
	v_cmp_le_i32_e32 vcc, v3, v186
	v_subrev_u32_e32 v3, 20, v2
	s_nop 0
	v_cndmask_b32_e32 v118, v232, v118, vcc
	v_cmp_le_i32_e32 vcc, v3, v186
	v_add_u32_e32 v3, -15, v2
	s_nop 0
	v_cndmask_b32_e32 v119, v232, v119, vcc
	v_cmp_le_i32_e32 vcc, v3, v186
	v_add_u32_e32 v3, -14, v2
	s_nop 0
	v_cndmask_b32_e32 v120, v232, v120, vcc
	v_cmp_le_i32_e32 vcc, v3, v186
	v_add_u32_e32 v3, -13, v2
	s_nop 0
	v_cndmask_b32_e32 v121, v232, v121, vcc
	v_cmp_le_i32_e32 vcc, v3, v186
	v_add_u32_e32 v3, -12, v2
	s_nop 0
	v_cndmask_b32_e32 v122, v232, v122, vcc
	v_cmp_le_i32_e32 vcc, v3, v186
	v_add_u32_e32 v3, -7, v2
	s_nop 0
	v_cndmask_b32_e32 v123, v232, v123, vcc
	v_cmp_le_i32_e32 vcc, v3, v186
	v_add_u32_e32 v3, -6, v2
	s_nop 0
	v_cndmask_b32_e32 v124, v232, v124, vcc
	v_cmp_le_i32_e32 vcc, v3, v186
	v_add_u32_e32 v3, -5, v2
	v_add_u32_e32 v2, -4, v2
	v_cndmask_b32_e32 v125, v232, v125, vcc
	v_cmp_le_i32_e32 vcc, v3, v186
	s_nop 1
	v_cndmask_b32_e32 v126, v232, v126, vcc
	v_cmp_le_i32_e32 vcc, v2, v186
	s_nop 1
	v_cndmask_b32_e32 v127, v232, v127, vcc

; template <int DQK, int W1, int DV, int VW, int MODE> ...
;     ...
;       float mx = s[0][0];
; #pragma unroll
;       for (int i = 1; i < 16; ++i) mx = fmaxf(mx, s[0][i]);
; #pragma unroll
;       for (int i = 0; i < 16; ++i) mx = fmaxf(mx, s[1][i]);
;       mx = xhalf_max(mx);
;       if (MODE == 0) {
;         if (t == 0) {
;           m = mx;
;           s[0] = s[0] - mx; s[1] = s[1] - mx; negm = negm - mx;
;         } else if (__any(mx > 8.0f)) {
;           const float d = fmaxf(mx, 0.f), alpha = __builtin_amdgcn_exp2f(-d);
;           m += d; l *= alpha;
;           s[0] = s[0] - d; s[1] = s[1] - d; negm = negm - d;
; #pragma unroll
;           for (int cb = 0; cb < NCB; ++cb)
; #pragma unroll
;             for (int r = 0; r < 16; ++r) o[cb][r] *= alpha;
;         }
;       } else if (__any(mx - m > 8.0f)) {
;         const float mnew = fmaxf(m, mx), alpha = __builtin_amdgcn_exp2f(m - mnew);
;         m = mnew; l *= alpha;
; #pragma unroll
;         for (int cb = 0; cb < NCB; ++cb)
; #pragma unroll
;           for (int r = 0; r < 16; ++r) o[cb][r] *= alpha;
;       }
;       {
;         f32x16 e0 = s[0], e1 = s[1];
;         if (MODE != 0) { const float nm = -m; e0 = e0 + nm; e1 = e1 + nm; }
; #pragma unroll
;         for (int i = 0; i < 16; ++i) { e0[i] = __builtin_amdgcn_exp2f(e0[i]); e1[i] = __builtin_amdgcn_exp2f(e1[i]); }
.Lmla_nd:
	ds_read_b128 v[2:5], v14
	ds_read_b128 v[6:9], v14 offset:32
	ds_read_b128 v[10:13], v14 offset:64
	ds_read_b128 v[112:115], v14 offset:96
	s_waitcnt lgkmcnt(3)
	v_mfma_f32_32x32x16_bf16 v[96:111], v[2:5], v[128:131], v[80:95]
	ds_read_b128 v[2:5], v14 offset:128
	s_waitcnt lgkmcnt(3)
	v_mfma_f32_32x32x16_bf16 v[96:111], v[6:9], v[132:135], v[96:111]
	ds_read_b128 v[6:9], v14 offset:160
	s_waitcnt lgkmcnt(3)
	v_mfma_f32_32x32x16_bf16 v[96:111], v[10:13], v[136:139], v[96:111]
	ds_read_b128 v[10:13], v14 offset:192
	s_waitcnt lgkmcnt(3)
	v_mfma_f32_32x32x16_bf16 v[96:111], v[112:115], v[140:143], v[96:111]
	ds_read_b128 v[112:115], v14 offset:224
	s_waitcnt lgkmcnt(3)
	v_mfma_f32_32x32x16_bf16 v[96:111], v[2:5], v[144:147], v[96:111]
	ds_read_b128 v[2:5], v14 offset:256
	s_waitcnt lgkmcnt(3)
	v_mfma_f32_32x32x16_bf16 v[96:111], v[6:9], v[148:151], v[96:111]
	ds_read_b128 v[6:9], v14 offset:288
	s_waitcnt lgkmcnt(3)
	v_mfma_f32_32x32x16_bf16 v[96:111], v[10:13], v[152:155], v[96:111]
	ds_read_b128 v[10:13], v14 offset:320
	s_waitcnt lgkmcnt(3)
	v_mfma_f32_32x32x16_bf16 v[96:111], v[112:115], v[156:159], v[96:111]
	ds_read_b128 v[112:115], v14 offset:352
	s_waitcnt lgkmcnt(3)
	v_mfma_f32_32x32x16_bf16 v[96:111], v[2:5], v[160:163], v[96:111]
	ds_read_b128 v[2:5], v14 offset:12800
	s_waitcnt lgkmcnt(3)
	v_mfma_f32_32x32x16_bf16 v[96:111], v[6:9], v[164:167], v[96:111]
	ds_read_b128 v[6:9], v14 offset:12832
	s_waitcnt lgkmcnt(3)
	v_mfma_f32_32x32x16_bf16 v[96:111], v[10:13], v[168:171], v[96:111]
	ds_read_b128 v[10:13], v14 offset:12864
	s_waitcnt lgkmcnt(3)
	v_mfma_f32_32x32x16_bf16 v[96:111], v[112:115], v[172:175], v[96:111]
	ds_read_b128 v[208:211], v14 offset:12896
	s_waitcnt lgkmcnt(3)
	v_mfma_f32_32x32x16_bf16 v[112:127], v[2:5], v[128:131], v[80:95]
	ds_read_b128 v[2:5], v14 offset:12928
	s_waitcnt lgkmcnt(3)
	v_mfma_f32_32x32x16_bf16 v[112:127], v[6:9], v[132:135], v[112:127]
	s_nop 3
	v_max_f32_e32 v241, v96, v97
	v_max3_f32 v241, v241, v98, v99
	ds_read_b128 v[6:9], v14 offset:12960
	s_waitcnt lgkmcnt(3)
	v_mfma_f32_32x32x16_bf16 v[112:127], v[10:13], v[136:139], v[112:127]
	v_max3_f32 v241, v241, v100, v101
	v_max3_f32 v241, v241, v102, v103
	ds_read_b128 v[10:13], v14 offset:12992
	s_waitcnt lgkmcnt(3)
	v_mfma_f32_32x32x16_bf16 v[112:127], v[208:211], v[140:143], v[112:127]
	v_max3_f32 v241, v241, v104, v105
	v_max3_f32 v241, v241, v106, v107
	ds_read_b128 v[208:211], v14 offset:13024
	s_waitcnt lgkmcnt(3)
	v_mfma_f32_32x32x16_bf16 v[112:127], v[2:5], v[144:147], v[112:127]
	v_max3_f32 v241, v241, v108, v109
	v_max3_f32 v241, v241, v110, v111
	ds_read_b128 v[2:5], v14 offset:13056
	s_waitcnt lgkmcnt(3)
	v_mfma_f32_32x32x16_bf16 v[112:127], v[6:9], v[148:151], v[112:127]
	v_exp_f32_e32 v96, v96
	v_exp_f32_e32 v97, v97
	ds_read_b128 v[6:9], v14 offset:13088
	s_waitcnt lgkmcnt(3)
	v_mfma_f32_32x32x16_bf16 v[112:127], v[10:13], v[152:155], v[112:127]
	v_exp_f32_e32 v98, v98
	v_exp_f32_e32 v99, v99
	ds_read_b128 v[10:13], v14 offset:13120
	s_waitcnt lgkmcnt(3)
	v_mfma_f32_32x32x16_bf16 v[112:127], v[208:211], v[156:159], v[112:127]
	v_exp_f32_e32 v100, v100
	v_exp_f32_e32 v101, v101
	ds_read_b128 v[208:211], v14 offset:13152
	s_waitcnt lgkmcnt(3)
	v_mfma_f32_32x32x16_bf16 v[112:127], v[2:5], v[160:163], v[112:127]
	v_exp_f32_e32 v102, v102
	v_exp_f32_e32 v103, v103
	s_waitcnt lgkmcnt(2)
	v_mfma_f32_32x32x16_bf16 v[112:127], v[6:9], v[164:167], v[112:127]
	v_exp_f32_e32 v104, v104
	v_exp_f32_e32 v105, v105
	s_waitcnt lgkmcnt(1)
	v_mfma_f32_32x32x16_bf16 v[112:127], v[10:13], v[168:171], v[112:127]
	v_exp_f32_e32 v106, v106
	v_exp_f32_e32 v107, v107
	s_waitcnt lgkmcnt(0)
	v_mfma_f32_32x32x16_bf16 v[112:127], v[208:211], v[172:175], v[112:127]
	v_exp_f32_e32 v108, v108
	v_exp_f32_e32 v109, v109
	v_exp_f32_e32 v110, v110
	v_exp_f32_e32 v111, v111
	s_nop 3
	v_max_f32_e32 v2, v112, v113
	v_max3_f32 v2, v2, v114, v115
	v_max3_f32 v2, v2, v116, v117
	v_max3_f32 v2, v2, v118, v119
	v_max3_f32 v2, v2, v120, v121
	v_max3_f32 v2, v2, v122, v123
	v_max3_f32 v2, v2, v124, v125
	v_max3_f32 v2, v2, v126, v127
	v_max_f32_e32 v2, v2, v241
	v_mov_b32_e32 v3, v2
	s_nop 1
	v_permlane32_swap_b32_e32 v2, v3
	v_max_f32_e32 v2, v2, v3
	v_cmp_lt_f32_e32 vcc, s21, v2
	s_cbranch_vccnz .Lmla_nd_rare
; template <int DQK, int W1, int DV, int VW, int MODE> ...
;     ...
;         } else if (__any(mx > 8.0f)) {
;           const float d = fmaxf(mx, 0.f), alpha = __builtin_amdgcn_exp2f(-d);
;           m += d; l *= alpha;
;           s[0] = s[0] - d; s[1] = s[1] - d; negm = negm - d;
; #pragma unroll
;           for (int cb = 0; cb < NCB; ++cb)
; #pragma unroll
;             for (int r = 0; r < 16; ++r) o[cb][r] *= alpha;
;         }
;       } else if (__any(mx - m > 8.0f)) {
;         const float mnew = fmaxf(m, mx), alpha = __builtin_amdgcn_exp2f(m - mnew);
;         m = mnew; l *= alpha;
; #pragma unroll
;         for (int cb = 0; cb < NCB; ++cb)
; #pragma unroll
;           for (int r = 0; r < 16; ++r) o[cb][r] *= alpha;
;       }
;       {
;         f32x16 e0 = s[0], e1 = s[1];
;         if (MODE != 0) { const float nm = -m; e0 = e0 + nm; e1 = e1 + nm; }
; #pragma unroll
;         for (int i = 0; i < 16; ++i) { e0[i] = __builtin_amdgcn_exp2f(e0[i]); e1[i] = __builtin_amdgcn_exp2f(e1[i]); }
;         s[0] = e0; s[1] = e1;
;         const f32x16 sm = e0 + e1;
;         typedef __attribute__((ext_vector_type(8))) float f32x8;
;         const f32x8 h8 = sm.lo + sm.hi;
;         const f32x4 h4 = h8.lo + h8.hi;
;         const f32x2 h2 = h4.lo + h4.hi;
;         l += h2[0] + h2[1];
;       }
;       bf16x8 pb[2][2];
; #pragma unroll
;       for (int n = 0; n < 2; ++n)
; #pragma unroll
;         for (int s2 = 0; s2 < 2; ++s2) {
;           u32x4 pw = {pk2(s[n][8 * s2 + 0], s[n][8 * s2 + 1]), pk2(s[n][8 * s2 + 2], s[n][8 * s2 + 3]),
;                       pk2(s[n][8 * s2 + 4], s[n][8 * s2 + 5]), pk2(s[n][8 * s2 + 6], s[n][8 * s2 + 7])};
;           pb[n][s2] = __builtin_bit_cast(bf16x8, pw);
;         }
.Lmla_nd_e:
	v_exp_f32_e32 v112, v112
	v_exp_f32_e32 v113, v113
	v_exp_f32_e32 v114, v114
	v_exp_f32_e32 v115, v115
	v_exp_f32_e32 v116, v116
	v_exp_f32_e32 v117, v117
	v_exp_f32_e32 v118, v118
	v_exp_f32_e32 v119, v119
	v_exp_f32_e32 v120, v120
	v_exp_f32_e32 v121, v121
	v_exp_f32_e32 v122, v122
	v_exp_f32_e32 v123, v123
	v_exp_f32_e32 v124, v124
	v_exp_f32_e32 v125, v125
	v_exp_f32_e32 v126, v126
	v_exp_f32_e32 v127, v127
	v_pk_add_f32 v[212:213], v[96:97], v[98:99]
	v_pk_add_f32 v[214:215], v[100:101], v[102:103]
	v_pk_add_f32 v[216:217], v[104:105], v[106:107]
	v_pk_add_f32 v[208:209], v[108:109], v[110:111]
	v_pk_add_f32 v[210:211], v[112:113], v[114:115]
	v_pk_add_f32 v[242:243], v[116:117], v[118:119]
	v_pk_add_f32 v[14:15], v[120:121], v[122:123]
	v_pk_add_f32 v[212:213], v[212:213], v[214:215]
	v_pk_add_f32 v[214:215], v[124:125], v[126:127]
	v_cvt_pk_bf16_f32 v96, v96, v97
	v_cvt_pk_bf16_f32 v97, v98, v99
	v_cvt_pk_bf16_f32 v98, v100, v101
	v_cvt_pk_bf16_f32 v99, v102, v103
	v_cvt_pk_bf16_f32 v10, v104, v105
	v_cvt_pk_bf16_f32 v11, v106, v107
	v_cvt_pk_bf16_f32 v12, v108, v109
	v_cvt_pk_bf16_f32 v13, v110, v111
	v_cvt_pk_bf16_f32 v6, v112, v113
	v_cvt_pk_bf16_f32 v7, v114, v115
	v_cvt_pk_bf16_f32 v8, v116, v117
	v_cvt_pk_bf16_f32 v9, v118, v119
	v_cvt_pk_bf16_f32 v2, v120, v121
	v_cvt_pk_bf16_f32 v3, v122, v123
	v_cvt_pk_bf16_f32 v4, v124, v125
	v_mov_b32_e32 v116, v126
	v_mov_b32_e32 v117, v127
	v_pk_add_f32 v[216:217], v[216:217], v[208:209]
	v_pk_add_f32 v[210:211], v[210:211], v[242:243]
	v_pk_add_f32 v[14:15], v[14:15], v[214:215]
	v_pk_add_f32 v[212:213], v[212:213], v[216:217]
	v_pk_add_f32 v[210:211], v[210:211], v[14:15]
	v_pk_add_f32 v[212:213], v[212:213], v[210:211]
	v_add_f32_e32 v118, v212, v213
	s_branch .Lmla_join
.Lmla_nd_rare:
	v_max_f32_e32 v3, 0, v2
	v_exp_f32_e64 v2, -v3
	s_nop 0
	v_mul_f32_e32 v96, v96, v2
	v_mul_f32_e32 v97, v97, v2
	v_mul_f32_e32 v98, v98, v2
	v_mul_f32_e32 v99, v99, v2
	v_mul_f32_e32 v100, v100, v2
	v_mul_f32_e32 v101, v101, v2
	v_mul_f32_e32 v102, v102, v2
	v_mul_f32_e32 v103, v103, v2
	v_mul_f32_e32 v104, v104, v2
	v_mul_f32_e32 v105, v105, v2
	v_mul_f32_e32 v106, v106, v2
	v_mul_f32_e32 v107, v107, v2
	v_mul_f32_e32 v108, v108, v2
	v_mul_f32_e32 v109, v109, v2
	v_mul_f32_e32 v110, v110, v2
	v_mul_f32_e32 v111, v111, v2
	v_sub_f32_e32 v112, v112, v3
	v_sub_f32_e32 v113, v113, v3
	v_sub_f32_e32 v114, v114, v3
	v_sub_f32_e32 v115, v115, v3
	v_sub_f32_e32 v116, v116, v3
	v_sub_f32_e32 v117, v117, v3
	v_sub_f32_e32 v118, v118, v3
	v_sub_f32_e32 v119, v119, v3
	v_sub_f32_e32 v120, v120, v3
	v_sub_f32_e32 v121, v121, v3
	v_sub_f32_e32 v122, v122, v3
	v_sub_f32_e32 v123, v123, v3
	v_sub_f32_e32 v124, v124, v3
	v_sub_f32_e32 v125, v125, v3
	v_sub_f32_e32 v126, v126, v3
	v_sub_f32_e32 v127, v127, v3
	v_pk_mul_f32 v[78:79], v[78:79], v[2:3] op_sel_hi:[1,0]
	v_pk_mul_f32 v[76:77], v[76:77], v[2:3] op_sel_hi:[1,0]
	v_pk_mul_f32 v[74:75], v[74:75], v[2:3] op_sel_hi:[1,0]
	v_pk_mul_f32 v[72:73], v[72:73], v[2:3] op_sel_hi:[1,0]
	v_pk_mul_f32 v[70:71], v[70:71], v[2:3] op_sel_hi:[1,0]
	v_pk_mul_f32 v[68:69], v[68:69], v[2:3] op_sel_hi:[1,0]
	v_pk_mul_f32 v[66:67], v[66:67], v[2:3] op_sel_hi:[1,0]
	v_pk_mul_f32 v[64:65], v[64:65], v[2:3] op_sel_hi:[1,0]
	v_pk_mul_f32 v[62:63], v[62:63], v[2:3] op_sel_hi:[1,0]
	v_pk_mul_f32 v[60:61], v[60:61], v[2:3] op_sel_hi:[1,0]
	v_pk_mul_f32 v[58:59], v[58:59], v[2:3] op_sel_hi:[1,0]
	v_pk_mul_f32 v[56:57], v[56:57], v[2:3] op_sel_hi:[1,0]
	v_pk_mul_f32 v[54:55], v[54:55], v[2:3] op_sel_hi:[1,0]
	v_pk_mul_f32 v[52:53], v[52:53], v[2:3] op_sel_hi:[1,0]
	v_pk_mul_f32 v[50:51], v[50:51], v[2:3] op_sel_hi:[1,0]
	v_pk_mul_f32 v[48:49], v[48:49], v[2:3] op_sel_hi:[1,0]
	v_pk_mul_f32 v[46:47], v[46:47], v[2:3] op_sel_hi:[1,0]
	v_pk_mul_f32 v[44:45], v[44:45], v[2:3] op_sel_hi:[1,0]
	v_pk_mul_f32 v[42:43], v[42:43], v[2:3] op_sel_hi:[1,0]
	v_pk_mul_f32 v[40:41], v[40:41], v[2:3] op_sel_hi:[1,0]
	v_pk_mul_f32 v[38:39], v[38:39], v[2:3] op_sel_hi:[1,0]
	v_pk_mul_f32 v[36:37], v[36:37], v[2:3] op_sel_hi:[1,0]
	v_pk_mul_f32 v[34:35], v[34:35], v[2:3] op_sel_hi:[1,0]
	v_pk_mul_f32 v[32:33], v[32:33], v[2:3] op_sel_hi:[1,0]
	v_pk_mul_f32 v[30:31], v[30:31], v[2:3] op_sel_hi:[1,0]
	v_pk_mul_f32 v[28:29], v[28:29], v[2:3] op_sel_hi:[1,0]
	v_pk_mul_f32 v[26:27], v[26:27], v[2:3] op_sel_hi:[1,0]
	v_pk_mul_f32 v[24:25], v[24:25], v[2:3] op_sel_hi:[1,0]
	v_pk_mul_f32 v[22:23], v[22:23], v[2:3] op_sel_hi:[1,0]
	v_pk_mul_f32 v[20:21], v[20:21], v[2:3] op_sel_hi:[1,0]
	v_pk_mul_f32 v[18:19], v[18:19], v[2:3] op_sel_hi:[1,0]
	v_pk_mul_f32 v[16:17], v[16:17], v[2:3] op_sel_hi:[1,0]
	v_mul_f32_e32 v236, v236, v2
	v_sub_f32_e32 v95, v95, v3
	v_sub_f32_e32 v94, v94, v3
	v_sub_f32_e32 v93, v93, v3
	v_sub_f32_e32 v92, v92, v3
	v_sub_f32_e32 v91, v91, v3
	v_sub_f32_e32 v90, v90, v3
	v_sub_f32_e32 v89, v89, v3
	v_sub_f32_e32 v88, v88, v3
	v_sub_f32_e32 v87, v87, v3
	v_sub_f32_e32 v86, v86, v3
	v_sub_f32_e32 v85, v85, v3
	v_sub_f32_e32 v84, v84, v3
	v_sub_f32_e32 v83, v83, v3
	v_sub_f32_e32 v82, v82, v3
	v_sub_f32_e32 v81, v81, v3
	v_sub_f32_e32 v80, v80, v3
	s_branch .Lmla_nd_e
